# first grid sync: arrive on the runtime barrier at kernel start, check its release after phase 0, then sync on the device-memory two-level barrier
# speedup vs baseline: 1.0358x; 1.0024x over previous
; __device__ __forceinline__ int opaque_bid() { int t = blockIdx.x; asm volatile("" : "+s"(t)); return t; }
; __device__ __forceinline__ void convert_in_tail(const Params& p, unsigned char* smem, int n_units, int t_begin, int t_end) {
;     const int G = gridDim.x, rem = n_units % G, bid = opaque_bid();
;     if (rem == 0) convert_tiles(p, smem, t_begin, t_end, bid, G);
;     else if (bid >= rem) convert_tiles(p, smem, t_begin, t_end, bid - rem, G - rem);
; __global__ void __launch_bounds__(512, 2) hymba_fwd(Params p0) {
;     extern __shared__ __attribute__((aligned(16))) unsigned char smem[];
;     cg::grid_group grid = cg::this_grid();
;     ...
;     for (int phx = p0.ph_lo; phx < p0.ph_hi + (DUP_PHASE >= 0 ? 1 : 0); ++phx) {
;         const int ph = (DUP_PHASE >= 0 && phx > DUP_PHASE) ? phx - 1 : phx;
;         Params p = p0;
;         { size_t z = 0; asm volatile("" : "+s"(z)); p.ws = p0.ws + z; p.out = p0.out + z; }
.LBB0_1:
	s_load_dword s7, s[0:1], 0xf0
	s_load_dwordx4 s[8:11], s[0:1], 0xd8
	s_add_u32 s2, s0, 0xf0
	s_addc_u32 s3, s1, 0
	v_writelane_b32 v254, s2, 3
	v_and_b32_e32 v151, 0x3ff, v0
	v_and_b32_e32 v4, 0x3fffffff, v0
	v_writelane_b32 v254, s3, 4
	s_waitcnt lgkmcnt(0)
	s_abs_i32 s2, s7
	v_cvt_f32_u32_e32 v1, s2
	s_ashr_i32 s3, s7, 31
	v_writelane_b32 v254, s3, 5
	s_lshl_b32 s3, s7, 3
	v_rcp_iflag_f32_e32 v1, v1
	v_writelane_b32 v254, s3, 6
	s_sub_i32 s3, 0, s2
	s_lshl_b32 s47, s7, 9
	v_mul_f32_e32 v0, 0x4f7ffffe, v1
	v_cvt_u32_f32_e32 v0, v0
	v_mov_b32_e32 v149, 0
	v_mov_b32_e32 v152, 1.0
	v_mbcnt_lo_u32_b32 v205, -1, 0
	v_readfirstlane_b32 s4, v0
	s_mul_i32 s3, s3, s4
	s_mul_hi_u32 s3, s4, s3
	s_add_i32 s4, s4, s3
	s_mul_hi_u32 s3, s4, 0x65c
	s_mul_i32 s3, s3, s2
	s_sub_i32 s3, 0x65c, s3
	s_sub_i32 s6, s3, s2
	s_cmp_ge_u32 s3, s2
	s_cselect_b32 s3, s6, s3
	s_sub_i32 s6, s3, s2
	s_cmp_ge_u32 s3, s2
	s_cselect_b32 s3, s6, s3
	s_cmp_lg_u32 s3, 0
	s_cselect_b64 s[12:13], -1, 0
	v_writelane_b32 v254, s12, 7
	s_mul_hi_u32 s5, s4, 0x128
	s_mul_i32 s5, s5, s2
	v_writelane_b32 v254, s13, 8
	v_writelane_b32 v254, s3, 9
	s_sub_i32 s3, s7, s3
	v_writelane_b32 v254, s3, 10
	s_sub_i32 s3, 0x128, s5
	s_sub_i32 s5, s3, s2
	s_cmp_ge_u32 s3, s2
	s_cselect_b32 s3, s5, s3
	s_sub_i32 s5, s3, s2
	s_cmp_ge_u32 s3, s2
	s_cselect_b32 s3, s5, s3
	s_cmp_lg_u32 s3, 0
	s_cselect_b64 s[12:13], -1, 0
	v_writelane_b32 v254, s12, 11
	s_mov_b32 s91, 0x42a00000
	v_mov_b32_e32 v202, 0x358637bd
	v_writelane_b32 v254, s13, 12
	v_writelane_b32 v254, s3, 13
	s_sub_i32 s3, s7, s3
	v_writelane_b32 v254, s3, 14
	s_mul_hi_u32 s3, s4, 0x637
	s_mul_i32 s3, s3, s2
	s_sub_i32 s3, 0x637, s3
	s_sub_i32 s4, s3, s2
	s_cmp_ge_u32 s3, s2
	s_cselect_b32 s3, s4, s3
	s_sub_i32 s4, s3, s2
	s_cmp_ge_u32 s3, s2
	s_cselect_b32 s2, s4, s3
	s_cmp_lg_u32 s2, 0
	s_cselect_b64 s[4:5], -1, 0
	v_writelane_b32 v254, s4, 15
	v_mov_b32_e32 v150, 0x3ecc95a3
	v_mov_b32_e32 v203, 0x154ba000
	v_writelane_b32 v254, s5, 16
	v_writelane_b32 v254, s2, 17
	s_sub_i32 s2, s7, s2
	v_writelane_b32 v254, s2, 18
	s_add_u32 s2, s10, 0xec00000
	v_writelane_b32 v254, s2, 19
	s_addc_u32 s2, s11, 0
	s_bitcmp1_b32 s7, 0
	v_writelane_b32 v254, s2, 20
	s_cselect_b64 s[2:3], -1, 0
	v_writelane_b32 v254, s2, 21
	v_mov_b32_e32 v204, 1
	v_mov_b64_e32 v[154:155], 0x128
	v_writelane_b32 v254, s3, 22
	s_add_u32 s2, s10, 0xa200000
	v_writelane_b32 v254, s2, 23
	s_addc_u32 s2, s11, 0
	v_writelane_b32 v254, s2, 24
	s_add_u32 s2, s8, 0x543a180
	v_writelane_b32 v254, s2, 25
	v_writelane_b32 v254, s8, 26
	s_addc_u32 s2, s9, 0
	v_mov_b64_e32 v[156:157], 0x127
	v_writelane_b32 v254, s9, 27
	v_writelane_b32 v254, s10, 28
	v_writelane_b32 v254, s11, 29
	v_writelane_b32 v254, s2, 30
	v_writelane_b32 v254, s7, 31
	s_lshl_b32 s2, s7, 14
	v_writelane_b32 v254, s2, 32
	s_add_i32 s2, 0, 0x23d00
	v_writelane_b32 v254, s2, 33
	s_add_i32 s2, 0, 0x22c00
	v_writelane_b32 v254, s2, 34
	v_cmp_eq_u32_e64 s[2:3], 0, v4
	s_load_dwordx4 s[4:7], s[0:1], 0xc0
	v_mbcnt_hi_u32_b32 v206, -1, v205
	v_writelane_b32 v254, s2, 35
	v_mov_b32_e32 v207, 0x240e
	v_mov_b64_e32 v[158:159], 0x65b
	v_writelane_b32 v254, s3, 36
	s_load_dwordx2 s[2:3], s[0:1], 0xd0
	v_mov_b64_e32 v[160:161], 0x65c
	v_mov_b32_e32 v208, 0x2005
	v_mov_b32_e32 v209, 0x7fd
	v_mov_b32_e32 v0, v149
	s_waitcnt lgkmcnt(0)
	v_writelane_b32 v254, s2, 37
	v_mov_b32_e32 v1, v149
	v_mov_b32_e32 v2, v149
	v_writelane_b32 v254, s3, 38
	v_writelane_b32 v254, s4, 39
	v_mov_b32_e32 v3, v149
	v_mov_b32_e32 v162, 0x3f317218
	v_writelane_b32 v254, s5, 40
	v_writelane_b32 v254, s6, 41
	v_writelane_b32 v254, s7, 42
	s_load_dwordx16 s[4:19], s[0:1], 0x0
	v_mov_b32_e32 v210, 0x7f800000
	v_mov_b32_e32 v211, 0x7fc00000
	v_mov_b32_e32 v212, 0xff800000
	v_bfrev_b32_e32 v213, 0.5
	s_waitcnt lgkmcnt(0)
	v_writelane_b32 v254, s4, 43
	v_mov_b32_e32 v164, 1.0
	v_mov_b32_e32 v165, v152
	v_writelane_b32 v254, s5, 44
	v_writelane_b32 v254, s6, 45
	v_writelane_b32 v254, s7, 46
	v_writelane_b32 v254, s8, 47
	v_writelane_b32 v254, s9, 48
	v_writelane_b32 v254, s10, 49
	v_writelane_b32 v254, s11, 50
	v_writelane_b32 v254, s12, 51
	v_writelane_b32 v254, s13, 52
	v_writelane_b32 v254, s14, 53
	v_writelane_b32 v254, s15, 54
	v_writelane_b32 v254, s16, 55
	v_writelane_b32 v254, s17, 56
	v_writelane_b32 v254, s18, 57
	v_writelane_b32 v254, s19, 58
	s_load_dwordx16 s[4:19], s[0:1], 0x40
	v_mov_b64_e32 v[166:167], 0x636
	v_mov_b64_e32 v[168:169], 0x637
	s_movk_i32 s45, 0x5600
	s_add_i32 s49, 0, 0x1dc00
	s_waitcnt lgkmcnt(0)
	v_writelane_b32 v254, s4, 59
	s_add_i32 s51, 0, 0x11000
	s_add_i32 s53, 0, 0x19800
	v_writelane_b32 v255, s9, 0
	v_writelane_b32 v255, s10, 1
	v_writelane_b32 v255, s11, 2
	v_writelane_b32 v255, s12, 3
	v_writelane_b32 v255, s13, 4
	v_writelane_b32 v255, s14, 5
	v_writelane_b32 v255, s15, 6
	v_writelane_b32 v254, s5, 60
	v_writelane_b32 v255, s16, 7
	v_writelane_b32 v254, s6, 61
	v_writelane_b32 v255, s17, 8
	v_writelane_b32 v254, s7, 62
	v_writelane_b32 v255, s18, 9
	v_writelane_b32 v254, s8, 63
	v_writelane_b32 v255, s19, 10
	s_load_dwordx16 s[4:19], s[0:1], 0x80
	s_movk_i32 s55, 0x110
	s_mov_b32 s97, 0
	s_mov_b64 s[34:35], 0x80
	s_mov_b32 s90, 0x3db504f3
	s_waitcnt lgkmcnt(0)
	v_writelane_b32 v255, s4, 11
	s_mov_b32 s50, s47
	s_nop 0
	v_writelane_b32 v255, s5, 12
	v_writelane_b32 v255, s6, 13
	v_writelane_b32 v255, s7, 14
	v_writelane_b32 v255, s8, 15
	v_writelane_b32 v255, s9, 16
	v_writelane_b32 v255, s10, 17
	v_writelane_b32 v255, s11, 18
	v_writelane_b32 v255, s12, 19
	v_writelane_b32 v255, s13, 20
	v_writelane_b32 v255, s14, 21
	v_writelane_b32 v255, s15, 22
	v_writelane_b32 v255, s16, 23
	v_writelane_b32 v255, s17, 24
	v_writelane_b32 v255, s18, 25
	v_writelane_b32 v255, s19, 26
	s_mov_b32 s2, 0
	s_nop 0
	v_writelane_b32 v255, s2, 61
	v_writelane_b32 v255, s2, 63
	v_cmp_eq_u32_e32 vcc, 0, v151
	s_and_saveexec_b64 s[2:3], vcc
	s_cbranch_execz .Lpre_done
	v_readlane_b32 s8, v254, 3
	v_readlane_b32 s9, v254, 4
	s_nop 0
	s_load_dwordx2 s[8:9], s[8:9], 0x58
	v_readlane_b32 s4, v254, 28
	v_readlane_b32 s5, v254, 29
	v_readlane_b32 s7, v254, 0
	s_add_u32 s10, s4, 0x229f2000
	s_addc_u32 s11, s5, 0
	s_and_b32 s7, s7, 7
	s_lshl_b32 s7, s7, 8
	s_add_u32 s12, s10, s7
	s_addc_u32 s13, s11, 0
	global_atomic_and v149, v149, s[12:13] offset:256
	global_atomic_and v149, v149, s[12:13] offset:2560
	global_atomic_and v149, v149, s[10:11] offset:2304
	s_waitcnt vmcnt(0) lgkmcnt(0)
	global_load_dword v4, v149, s[8:9] offset:40
	v_mov_b32_e32 v6, 1
	s_nop 0
	global_atomic_add v6, v149, v6, s[8:9] offset:32 sc0
	s_waitcnt vmcnt(0)
	v_readfirstlane_b32 s4, v6
	v_readfirstlane_b32 s5, v4
	s_and_b32 s6, s4, 0xffff
	s_and_b32 s4, s4, 0xffff0000
	s_add_i32 s7, s5, -1
	v_writelane_b32 v255, s4, 59
	s_cmp_lg_u32 s6, s7
	s_cbranch_scc1 .Lpre_done
	s_sub_i32 s5, 0x10000, s5
	v_mov_b32_e32 v4, s5
	global_atomic_add v149, v4, s[8:9] offset:32
.Lpre_done:
	s_or_b64 exec, exec, s[2:3]
	s_movk_i32 s2, 0xb0
	s_nop 0
	v_writelane_b32 v254, s2, 9
	s_movk_i32 s2, 0x50
	s_nop 0
	v_writelane_b32 v254, s2, 10
	s_branch .LBB0_5

; __global__ void __launch_bounds__(512, 2) hymba_fwd(Params p0) {
;     ...
;         if (phx + 1 < p0.ph_hi + (DUP_PHASE >= 0 ? 1 : 0)) grid.sync();
.LBB0_952:
	v_readlane_b32 s2, v254, 3
	v_readlane_b32 s3, v254, 4
	buffer_wbl2 sc1
	s_load_dwordx2 s[8:9], s[2:3], 0x58
	v_readlane_b32 s4, v254, 28
	v_readlane_b32 s5, v254, 29
	v_readlane_b32 s6, v254, 1
	v_readlane_b32 s7, v254, 0
	s_add_u32 s10, s4, 0x229f2000
	s_addc_u32 s11, s5, 0
	s_and_b32 s7, s7, 7
	s_lshl_b32 s7, s7, 8
	s_add_u32 s12, s10, s7
	s_addc_u32 s13, s11, 0
	s_cmp_lg_u32 s6, 1
	s_cbranch_scc1 .Lgsync2
	v_readlane_b32 s4, v255, 59
	s_waitcnt lgkmcnt(0)
	s_mov_b32 s7, 0
.Lgsync_cg_wait:
	global_load_dword v5, v149, s[8:9] offset:32 sc1
	s_waitcnt vmcnt(0)
	v_readfirstlane_b32 s5, v5
	s_and_b32 s5, s5, 0xffff0000
	s_cmp_lg_u32 s5, s4
	s_cbranch_scc1 .Lgsync2
	s_add_i32 s7, s7, 1
	s_cmp_ge_u32 s7, 0x20000
	s_cbranch_scc1 .Lgsync2
	s_sleep 1
	s_branch .Lgsync_cg_wait
